# static priority raise for waves 4-7 also inside the COMB token loop
# speedup vs baseline: 1.0195x; 1.0037x over previous
.LBB0_730:
	s_and_b64 vcc, exec, s[96:97]
	v_readlane_b32 s65, v254, 10
	s_cbranch_vccz .LBB0_867
	s_and_b32 s0, s59, -2
	s_cmp_lg_u32 s0, 8
	s_mov_b64 s[0:1], -1
	s_cbranch_scc0 .LBB0_757
	s_cmp_lt_i32 s59, 11
	s_cbranch_scc1 .LBB0_739
	s_cmp_eq_u32 s59, 11
	s_cbranch_scc0 .LBB0_738
	s_mov_b64 s[0:1], 0
	s_waitcnt vmcnt(0)
	v_mov_b32_e32 v0, v202
	v_readlane_b32 s4, v251, 0
	v_mov_b32_e32 v2, v202
	s_lshl_b32 s6, s4, 3
	v_ashrrev_i32_e32 v2, 6, v2
	v_add_u32_e32 v10, s6, v2
	s_movk_i32 s4, 0x4000
	v_cmp_gt_i32_e32 vcc, s4, v10
	s_and_saveexec_b64 s[4:5], vcc
	v_readlane_b32 s10, v253, 44
	v_readlane_b32 s11, v253, 45
	v_readlane_b32 s30, v253, 46
	v_readlane_b32 s34, v252, 54
	v_readlane_b32 s31, v253, 47
	s_movk_i32 s11, 0x3fff
	v_readlane_b32 s35, v252, 55
	s_mov_b64 s[36:37], 0x16000000
	s_cbranch_execz .LBB0_737
	s_waitcnt lgkmcnt(0)
	v_ashrrev_i32_e32 v3, 31, v2
	s_ashr_i32 s7, s6, 31
	s_waitcnt lgkmcnt(0)
	v_lshl_add_u64 v[8:9], v[2:3], 0, s[6:7]
	v_lshlrev_b64 v[2:3], 11, v[8:9]
	v_and_b32_e32 v11, 63, v0
	v_lshlrev_b64 v[8:9], 6, v[8:9]
	v_lshl_or_b32 v2, v11, 5, v2
	v_and_or_b32 v8, v0, 60, v8
	v_lshl_add_u64 v[2:3], s[26:27], 0, v[2:3]
	v_lshl_add_u64 v[8:9], s[26:27], 0, v[8:9]
	s_mov_b64 s[6:7], 0
	v_readfirstlane_b32 s101, v202
	s_nop 3
	s_lshr_b32 s101, s101, 6
	s_cmp_ge_u32 s101, 4
	s_cbranch_scc0 .Lcomb_prio_done
	s_setprio 1
.Lcomb_prio_done:
.LBB0_736:
	v_lshl_add_u64 v[12:13], v[8:9], 0, s[0:1]
	v_add_co_u32_e32 v14, vcc, 0x1a000000, v12
	v_lshl_add_u64 v[40:41], v[2:3], 0, s[0:1]
	s_nop 0
	v_addc_co_u32_e32 v15, vcc, 0, v13, vcc
	global_load_dword v0, v[14:15], off
	v_add_co_u32_e32 v14, vcc, 0x1a100000, v12
	v_lshl_add_u64 v[24:25], v[40:41], 0, s[36:37]
	s_nop 0
	v_addc_co_u32_e32 v15, vcc, 0, v13, vcc
	v_add_co_u32_e32 v12, vcc, 0x1a200000, v12
	global_load_dword v47, v[14:15], off
	s_nop 0
	v_addc_co_u32_e32 v13, vcc, 0, v13, vcc
	global_load_dword v48, v[12:13], off
	v_add_u32_e32 v10, s10, v10
	v_lshl_add_u64 v[2:3], v[2:3], 0, s[34:35]
	v_lshl_add_u64 v[8:9], v[8:9], 0, s[30:31]
	s_mov_b64 s[8:9], 0x14000000
	v_lshl_add_u64 v[16:17], v[40:41], 0, s[8:9]
	s_brev_b32 s8, 40
	v_add_co_u32_e32 v12, vcc, s8, v40
	s_mov_b32 s8, 0x16000000
	s_nop 0
	v_addc_co_u32_e32 v13, vcc, 0, v41, vcc
	v_add_co_u32_e32 v20, vcc, s8, v40
	s_mov_b64 s[8:9], 0x18000000
	s_nop 0
	v_addc_co_u32_e32 v21, vcc, 0, v41, vcc
	v_lshl_add_u64 v[32:33], v[40:41], 0, s[8:9]
	s_brev_b32 s8, 24
	global_load_dwordx4 v[12:15], v[12:13], off
	s_nop 0
	global_load_dwordx4 v[16:19], v[16:17], off offset:16
	s_nop 0
	global_load_dwordx4 v[20:23], v[20:21], off
	s_nop 0
	global_load_dwordx4 v[24:27], v[24:25], off offset:16
	v_add_co_u32_e32 v28, vcc, s8, v40
	s_nop 0
	v_addc_co_u32_e32 v29, vcc, 0, v41, vcc
	global_load_dwordx4 v[28:31], v[28:29], off
	s_nop 0
	global_load_dwordx4 v[32:35], v[32:33], off offset:16
	s_waitcnt vmcnt(6)
	v_max3_f32 v49, v0, v47, v48
	v_sub_f32_e32 v0, v0, v49
	v_mul_f32_e32 v0, 0x3fb8aa3b, v0
	v_exp_f32_e32 v37, v0
	v_sub_f32_e32 v0, v47, v49
	v_mul_f32_e32 v0, 0x3fb8aa3b, v0
	v_sub_f32_e32 v47, v48, v49
	v_exp_f32_e32 v0, v0
	v_mul_f32_e32 v47, 0x3fb8aa3b, v47
	v_exp_f32_e32 v36, v47
	v_add_f32_e32 v47, v37, v0
	v_add_f32_e32 v47, v36, v47
	v_div_scale_f32 v48, s[100:101], v47, v47, 1.0
	v_rcp_f32_e32 v49, v48
	s_nop 0
	v_fma_f32 v50, -v48, v49, 1.0
	v_fmac_f32_e32 v49, v50, v49
	v_div_scale_f32 v50, vcc, 1.0, v47, 1.0
	v_mul_f32_e32 v51, v50, v49
	v_fma_f32 v52, -v48, v51, v50
	v_fmac_f32_e32 v51, v52, v49
	v_fma_f32 v48, -v48, v51, v50
	v_div_fmas_f32 v48, v48, v49, v51
	v_div_fixup_f32 v38, v48, v47, 1.0
	v_mul_f32_e32 v0, v0, v38
	v_pk_mul_f32 v[36:37], v[36:37], v[38:39] op_sel_hi:[1,0]
	s_waitcnt vmcnt(5)
	v_lshlrev_b32_e32 v38, 16, v12
	s_waitcnt vmcnt(3)
	v_lshlrev_b32_e32 v42, 16, v20
	v_and_b32_e32 v43, 0xffff0000, v20
	v_lshlrev_b32_e32 v20, 16, v21
	v_and_b32_e32 v21, 0xffff0000, v21
	v_and_b32_e32 v39, 0xffff0000, v12
	v_lshlrev_b32_e32 v12, 16, v13
	v_and_b32_e32 v13, 0xffff0000, v13
	v_pk_mul_f32 v[20:21], v[0:1], v[20:21] op_sel_hi:[0,1]
	s_waitcnt vmcnt(1)
	v_lshlrev_b32_e32 v44, 16, v28
	v_and_b32_e32 v45, 0xffff0000, v28
	v_lshlrev_b32_e32 v28, 16, v29
	v_and_b32_e32 v29, 0xffff0000, v29
	v_pk_fma_f32 v[12:13], v[36:37], v[12:13], v[20:21] op_sel:[1,0,0]
	v_pk_mul_f32 v[42:43], v[0:1], v[42:43] op_sel_hi:[0,1]
	v_pk_fma_f32 v[20:21], v[36:37], v[28:29], v[12:13] op_sel_hi:[0,1,1]
	v_lshlrev_b32_e32 v28, 16, v22
	v_and_b32_e32 v29, 0xffff0000, v22
	v_lshlrev_b32_e32 v12, 16, v14
	v_and_b32_e32 v13, 0xffff0000, v14
	v_pk_mul_f32 v[28:29], v[0:1], v[28:29] op_sel_hi:[0,1]
	v_pk_fma_f32 v[38:39], v[36:37], v[38:39], v[42:43] op_sel:[1,0,0]
	v_lshlrev_b32_e32 v42, 16, v30
	v_and_b32_e32 v43, 0xffff0000, v30
	v_pk_fma_f32 v[12:13], v[36:37], v[12:13], v[28:29] op_sel:[1,0,0]
	v_lshlrev_b32_e32 v14, 16, v23
	v_pk_fma_f32 v[28:29], v[36:37], v[42:43], v[12:13] op_sel_hi:[0,1,1]
	v_lshlrev_b32_e32 v12, 16, v15
	v_and_b32_e32 v13, 0xffff0000, v15
	v_and_b32_e32 v15, 0xffff0000, v23
	v_lshlrev_b32_e32 v22, 16, v31
	v_and_b32_e32 v23, 0xffff0000, v31
	v_pk_mul_f32 v[14:15], v[0:1], v[14:15] op_sel_hi:[0,1]
	v_lshlrev_b32_e32 v30, 16, v24
	v_and_b32_e32 v31, 0xffff0000, v24
	v_pk_fma_f32 v[12:13], v[36:37], v[12:13], v[14:15] op_sel:[1,0,0]
	v_lshlrev_b32_e32 v14, 16, v16
	v_and_b32_e32 v15, 0xffff0000, v16
	v_pk_mul_f32 v[30:31], v[0:1], v[30:31] op_sel_hi:[0,1]
	s_waitcnt vmcnt(0)
	v_lshlrev_b32_e32 v42, 16, v32
	v_and_b32_e32 v43, 0xffff0000, v32
	v_pk_fma_f32 v[14:15], v[36:37], v[14:15], v[30:31] op_sel:[1,0,0]
	v_lshlrev_b32_e32 v16, 16, v25
	v_pk_fma_f32 v[30:31], v[36:37], v[42:43], v[14:15] op_sel_hi:[0,1,1]
	v_lshlrev_b32_e32 v14, 16, v17
	v_and_b32_e32 v15, 0xffff0000, v17
	v_and_b32_e32 v17, 0xffff0000, v25
	v_pk_mul_f32 v[16:17], v[0:1], v[16:17] op_sel_hi:[0,1]
	v_lshlrev_b32_e32 v24, 16, v33
	v_and_b32_e32 v25, 0xffff0000, v33
	v_pk_fma_f32 v[14:15], v[36:37], v[14:15], v[16:17] op_sel:[1,0,0]
	v_lshlrev_b32_e32 v16, 16, v26
	v_and_b32_e32 v17, 0xffff0000, v26
	v_pk_fma_f32 v[22:23], v[36:37], v[22:23], v[12:13] op_sel_hi:[0,1,1]
	v_and_b32_e32 v13, 0xffff0000, v19
	v_and_b32_e32 v12, 0xffff0000, v35
	v_pk_fma_f32 v[24:25], v[36:37], v[24:25], v[14:15] op_sel_hi:[0,1,1]
	v_lshlrev_b32_e32 v14, 16, v18
	v_and_b32_e32 v15, 0xffff0000, v18
	v_pk_mul_f32 v[16:17], v[0:1], v[16:17] op_sel_hi:[0,1]
	v_lshlrev_b32_e32 v11, 16, v19
	v_lshlrev_b32_e32 v18, 16, v34
	v_and_b32_e32 v19, 0xffff0000, v34
	v_pk_fma_f32 v[14:15], v[36:37], v[14:15], v[16:17] op_sel:[1,0,0]
	v_pk_mul_f32 v[12:13], v[36:37], v[12:13]
	v_pk_fma_f32 v[18:19], v[36:37], v[18:19], v[14:15] op_sel_hi:[0,1,1]
	v_mov_b32_e32 v15, v13
	v_cvt_pk_bf16_f32 v13, v20, v21
	v_add_co_u32_e32 v20, vcc, 0x27000000, v40
	v_lshlrev_b32_e32 v46, 16, v35
	v_mul_f32_e32 v14, v37, v11
	v_lshlrev_b32_e32 v26, 16, v27
	v_and_b32_e32 v27, 0xffff0000, v27
	v_addc_co_u32_e32 v21, vcc, 0, v41, vcc
	v_pk_fma_f32 v[38:39], v[36:37], v[44:45], v[38:39] op_sel_hi:[0,1,1]
	v_mul_f32_e32 v16, v36, v46
	v_pk_fma_f32 v[14:15], v[0:1], v[26:27], v[14:15] op_sel_hi:[0,1,1]
	v_mov_b32_e32 v17, v12
	v_cmp_lt_i32_e32 vcc, s11, v10
	v_pk_add_f32 v[26:27], v[16:17], v[14:15]
	v_cvt_pk_bf16_f32 v12, v38, v39
	v_cvt_pk_bf16_f32 v14, v28, v29
	v_cvt_pk_bf16_f32 v15, v22, v23
	s_or_b64 s[6:7], vcc, s[6:7]
	v_cvt_pk_bf16_f32 v16, v30, v31
	v_cvt_pk_bf16_f32 v17, v24, v25
	v_cvt_pk_bf16_f32 v18, v18, v19
	v_cvt_pk_bf16_f32 v19, v26, v27
	global_store_dwordx4 v[20:21], v[12:15], off
	global_store_dwordx4 v[20:21], v[16:19], off offset:16
	s_andn2_b64 exec, exec, s[6:7]
	s_cbranch_execnz .LBB0_736
.LBB0_737:
	s_setprio 0
	s_or_b64 exec, exec, s[4:5]
.LBB0_738:
	s_mov_b64 s[0:1], 0
